# v047 + gate-up next-unit descriptor short cut for a 256-workgroup grid (same panel, pn+4), generic division kept as fallback
# speedup vs baseline: 1.0058x; 1.0005x over previous
;     __host__ __device__ bool next(int i, Unit& u) const { Unit b; if (!base.next(i >> 1, b)) return false; u.pm = b.pm; u.pn = b.pn + 4 * (i & 1); return true; }
;     __host__ __device__ bool next(int i, Unit& u) const {
;         const long L = (long)i * G + c; if (L >= nwg) return false;
;         int wgid = (int)L; { const int q = nwg / NXCD, r = nwg % NXCD, xcd = wgid % NXCD, off = wgid / NXCD; wgid = (xcd < r ? xcd * (q + 1) : r * (q + 1) + (xcd - r) * q) + off; }
;         const int nig = WGM * nN, gid = wgid / nig, fm = gid * WGM, gsz = (nM - fm) < WGM ? (nM - fm) : WGM;
;         u.pm = fm + ((wgid % nig) % gsz); u.pn = (wgid % nig) / gsz; return true;
;     }
; template <class Epi, class Sched, bool ALIGN_EPI = false, bool SP2 = false, bool PAIR_ACC = false>
; __device__ __forceinline__ void gemm_phase(PG8_LAS unsigned char* lds, const Gemm g, const Sched& S, const Epi& E) {
;     ...
;         const bool has_next = S.next(ui + 1, nxt);
.LBB0_831:
	s_add_i32 s44, s44, 1
	s_mul_i32 s8, s44, s47
	s_mul_hi_u32 s9, s44, s3
	s_add_i32 s9, s9, s8
	s_mul_i32 s8, s44, s3
	s_add_u32 s40, s8, s2
	s_addc_u32 s41, s9, s34
	v_cmp_gt_i64_e32 vcc, s[40:41], v[192:193]
	v_cmp_lt_i64_e64 s[8:9], s[40:41], v[190:191]
	s_cbranch_vccnz .LBB0_833
	s_cmpk_lg_u32 s3, 0x100
	s_cbranch_scc1 .Lgnext_slow_0
	s_add_i32 s62, s71, 4
	s_mov_b32 s64, s70
	s_branch .LBB0_833
.Lgnext_slow_0:
	s_ashr_i32 s41, s40, 31
	s_lshr_b32 s41, s41, 29
	s_add_i32 s41, s40, s41
	s_ashr_i32 s62, s41, 3
	s_and_b32 s41, s41, -8
	s_sub_i32 s40, s40, s41
	s_cmp_lt_i32 s40, 0
	s_cselect_b32 s41, s35, 0xb0
	s_mul_i32 s40, s41, s40
	s_add_i32 s40, s40, s62
	s_mul_hi_i32 s41, s40, 0x2e8ba2e9
	s_lshr_b32 s62, s41, 31
	s_ashr_i32 s41, s41, 5
	s_add_i32 s41, s41, s62
	s_lshl_b32 s63, s41, 3
	s_sub_i32 s62, 64, s63
	s_min_i32 s64, s62, 8
	s_abs_i32 s62, s64
	v_cvt_f32_u32_e32 v2, s62
	s_sub_i32 s66, 0, s62
	s_mulk_i32 s41, 0xb0
	s_sub_i32 s40, s40, s41
	v_rcp_iflag_f32_e32 v2, v2
	s_abs_i32 s41, s40
	s_xor_b32 s65, s40, s64
	s_ashr_i32 s65, s65, 31
	v_mul_f32_e32 v2, 0x4f7ffffe, v2
	v_cvt_u32_f32_e32 v2, v2
	s_nop 0
	v_readfirstlane_b32 s67, v2
	s_mul_i32 s66, s66, s67
	s_mul_hi_u32 s66, s67, s66
	s_add_i32 s67, s67, s66
	s_mul_hi_u32 s66, s41, s67
	s_mul_i32 s67, s66, s62
	s_sub_i32 s41, s41, s67
	s_add_i32 s68, s66, 1
	s_sub_i32 s67, s41, s62
	s_cmp_ge_u32 s41, s62
	s_cselect_b32 s66, s68, s66
	s_cselect_b32 s41, s67, s41
	s_add_i32 s67, s66, 1
	s_cmp_ge_u32 s41, s62
	s_cselect_b32 s41, s67, s66
	s_xor_b32 s41, s41, s65
	s_sub_i32 s62, s41, s65
	s_mul_i32 s41, s62, s64
	s_sub_i32 s40, s40, s41
	s_add_i32 s64, s40, s63

;     __host__ __device__ bool next(int i, Unit& u) const { Unit b; if (!base.next(i >> 1, b)) return false; u.pm = b.pm; u.pn = b.pn + 4 * (i & 1); return true; }
;     __host__ __device__ bool next(int i, Unit& u) const {
;         const long L = (long)i * G + c; if (L >= nwg) return false;
;         int wgid = (int)L; { const int q = nwg / NXCD, r = nwg % NXCD, xcd = wgid % NXCD, off = wgid / NXCD; wgid = (xcd < r ? xcd * (q + 1) : r * (q + 1) + (xcd - r) * q) + off; }
;         const int nig = WGM * nN, gid = wgid / nig, fm = gid * WGM, gsz = (nM - fm) < WGM ? (nM - fm) : WGM;
;         u.pm = fm + ((wgid % nig) % gsz); u.pn = (wgid % nig) / gsz; return true;
;     }
; template <class Epi, class Sched, bool ALIGN_EPI = false, bool SP2 = false, bool PAIR_ACC = false>
; __device__ __forceinline__ void gemm_phase(PG8_LAS unsigned char* lds, const Gemm g, const Sched& S, const Epi& E) {
;     ...
;         const bool has_next = S.next(ui + 1, nxt);
.LBB0_1734:
	s_add_i32 s66, s66, 1
	s_mul_i32 s8, s66, s67
	s_mul_hi_u32 s9, s66, s3
	s_add_i32 s9, s9, s8
	s_mul_i32 s8, s66, s3
	s_add_u32 s10, s8, s2
	s_addc_u32 s11, s9, s65
	v_cmp_gt_i64_e32 vcc, s[10:11], v[190:191]
	v_cmp_lt_i64_e64 s[8:9], s[10:11], v[188:189]
	s_cbranch_vccnz .LBB0_1736
	s_cmpk_lg_u32 s3, 0x100
	s_cbranch_scc1 .Lgnext_slow_1
	s_add_i32 s50, s59, 4
	s_mov_b32 s52, s58
	s_branch .LBB0_1736
.Lgnext_slow_1:
	s_ashr_i32 s11, s10, 31
	s_lshr_b32 s11, s11, 29
	s_add_i32 s11, s10, s11
	s_ashr_i32 s50, s11, 3
	s_and_b32 s11, s11, -8
	s_sub_i32 s10, s10, s11
	s_cmp_lt_i32 s10, 0
	s_cselect_b32 s11, s35, 0xb0
	s_mul_i32 s10, s11, s10
	s_add_i32 s10, s10, s50
	s_mul_hi_i32 s11, s10, 0x2e8ba2e9
	s_lshr_b32 s50, s11, 31
	s_ashr_i32 s11, s11, 5
	s_add_i32 s11, s11, s50
	s_lshl_b32 s51, s11, 3
	s_sub_i32 s50, 64, s51
	s_min_i32 s52, s50, 8
	s_abs_i32 s50, s52
	v_cvt_f32_u32_e32 v2, s50
	s_sub_i32 s54, 0, s50
	s_mulk_i32 s11, 0xb0
	s_sub_i32 s10, s10, s11
	v_rcp_iflag_f32_e32 v2, v2
	s_abs_i32 s11, s10
	s_xor_b32 s53, s10, s52
	s_ashr_i32 s53, s53, 31
	v_mul_f32_e32 v2, 0x4f7ffffe, v2
	v_cvt_u32_f32_e32 v2, v2
	s_nop 0
	v_readfirstlane_b32 s55, v2
	s_mul_i32 s54, s54, s55
	s_mul_hi_u32 s54, s55, s54
	s_add_i32 s55, s55, s54
	s_mul_hi_u32 s54, s11, s55
	s_mul_i32 s55, s54, s50
	s_sub_i32 s11, s11, s55
	s_add_i32 s56, s54, 1
	s_sub_i32 s55, s11, s50
	s_cmp_ge_u32 s11, s50
	s_cselect_b32 s54, s56, s54
	s_cselect_b32 s11, s55, s11
	s_add_i32 s55, s54, 1
	s_cmp_ge_u32 s11, s50
	s_cselect_b32 s11, s55, s54
	s_xor_b32 s11, s11, s53
	s_sub_i32 s50, s11, s53
	s_mul_i32 s11, s50, s52
	s_sub_i32 s10, s10, s11
	s_add_i32 s52, s10, s51
